# GEMM phase prologues: K-tile 1 staging loads issued before the wait for K-tile 0 (vmcnt 2 -> 8)
# baseline (speedup 1.0000x reference)
.LBB0_96:
	s_add_u32 s30, s68, 0x1000000
	s_addc_u32 s31, s69, 0
	s_lshl_b32 s33, s8, 6
	s_lshl_b32 s38, s8, 13
	s_lshl_b32 s1, s1, 5
	s_mov_b64 s[8:9], 0x80
	s_and_b32 s34, s1, 0x60
	s_add_i32 m0, s25, 0x18000
	v_lshl_add_u64 v[6:7], v[6:7], 0, s[8:9]
	s_lshl_b32 s1, s34, 7
	global_load_lds_dwordx4 v[6:7], off
	v_lshl_add_u64 v[2:3], v[2:3], 0, s[8:9]
	s_add_i32 m0, s25, 0x1a000
	s_add_i32 s35, s25, 0x8000
	s_add_i32 s39, s25, 0xa000
	global_load_lds_dwordx4 v[2:3], off
	v_lshl_add_u64 v[0:1], v[0:1], 0, s[8:9]
	s_mov_b32 m0, s35
	s_add_u32 s36, s54, 0x40080
	global_load_lds_dwordx4 v[0:1], off
	v_lshl_add_u64 v[0:1], v[4:5], 0, s[8:9]
	s_mov_b32 m0, s39
	s_addc_u32 s37, s55, 0
	global_load_lds_dwordx4 v[0:1], off
	s_add_i32 m0, s25, 0x1c000
	v_lshl_add_u64 v[0:1], s[36:37], 0, v[130:131]
	global_load_lds_dwordx4 v[0:1], off
	v_lshl_add_u64 v[0:1], s[36:37], 0, v[134:135]
	s_add_i32 m0, s25, 0x1e000
	s_movk_i32 s36, 0x3c0
	global_load_lds_dwordx4 v[0:1], off
	s_waitcnt vmcnt(8)
	s_barrier
	v_and_b32_e32 v0, 48, v8
	v_lshlrev_b32_e32 v1, 6, v8
	v_and_or_b32 v0, v1, s36, v0
	v_lshlrev_b32_e32 v1, 2, v8
	v_and_b32_e32 v1, 32, v1
	v_bitop3_b32 v2, v0, s38, v1 bitop3:0xde
	v_bitop3_b32 v159, s1, v0, v1 bitop3:0xf6
	v_lshlrev_b32_e32 v0, 14, v9
	v_and_b32_e32 v0, 0xffff8000, v0
	v_lshl_add_u32 v0, v10, 11, v0
	v_and_b32_e32 v1, 1, v9
	v_lshl_or_b32 v0, v1, 6, v0
	v_lshl_add_u32 v138, v11, 1, v0
	v_lshlrev_b32_e32 v0, 14, v12
	v_and_b32_e32 v0, 0xffff8000, v0
	s_waitcnt vmcnt(6)
	s_cmpk_lt_u32 s3, 0x100
	v_lshl_add_u32 v0, v13, 11, v0
	v_and_b32_e32 v1, 1, v12
	s_cselect_b64 s[36:37], -1, 0
	v_lshl_or_b32 v0, v1, 6, v0
	s_add_i32 s60, 0, 0x10000
	s_add_i32 s61, 0, 0x14000
	v_and_b32_e32 v158, 63, v8
	v_mov_b32_e32 v139, v137
	v_lshl_add_u32 v140, v14, 1, v0
	v_mov_b32_e32 v141, v137
	v_add_u32_e32 v160, s60, v159
	v_add_u32_e32 v161, s61, v159
	v_add_u32_e32 v162, 0, v2
	s_mov_b32 s38, 0x3e000000
	s_barrier
	s_branch .LBB0_99

.LBB0_334:
	s_sext_i32_i8 s3, s6
	v_and_b32_e32 v180, 63, v14
	s_lshl_b32 s30, s8, 6
	v_and_b32_e32 v15, 48, v14
	s_lshl_b32 s6, s8, 13
	v_lshlrev_b32_e32 v16, 6, v14
	s_movk_i32 s8, 0x3c0
	v_lshlrev_b32_e32 v14, 2, v14
	v_and_or_b32 v15, v16, s8, v15
	v_and_b32_e32 v14, 32, v14
	v_bitop3_b32 v16, v15, s6, v14 bitop3:0xde
	s_lshl_b32 s6, s7, 5
	s_and_b32 s31, s6, 0x60
	s_lshl_b32 s6, s31, 7
	v_bitop3_b32 v181, s6, v15, v14 bitop3:0xf6
	s_mov_b64 s[6:7], 0x80
	s_add_i32 m0, s25, 0x18000
	v_lshl_add_u64 v[6:7], v[6:7], 0, s[6:7]
	global_load_lds_dwordx4 v[6:7], off
	v_lshl_add_u64 v[4:5], v[4:5], 0, s[6:7]
	s_add_i32 m0, s25, 0x1a000
	s_add_i32 s33, s25, 0x8000
	s_add_i32 s34, s25, 0xa000
	global_load_lds_dwordx4 v[4:5], off
	v_lshl_add_u64 v[0:1], v[0:1], 0, s[6:7]
	s_mov_b32 m0, s33
	s_add_u32 s8, s54, 0x20080
	global_load_lds_dwordx4 v[0:1], off
	v_lshl_add_u64 v[0:1], v[2:3], 0, s[6:7]
	s_mov_b32 m0, s34
	s_addc_u32 s9, s55, 0
	global_load_lds_dwordx4 v[0:1], off
	s_add_i32 m0, s25, 0x1c000
	v_lshl_add_u64 v[0:1], s[8:9], 0, v[164:165]
	global_load_lds_dwordx4 v[0:1], off
	v_lshl_add_u64 v[0:1], s[8:9], 0, v[160:161]
	s_add_i32 m0, s25, 0x1e000
	s_cmpk_lt_u32 s2, 0x100
	global_load_lds_dwordx4 v[0:1], off
	s_waitcnt vmcnt(8)
	s_barrier
	v_lshlrev_b32_e32 v0, 13, v12
	v_and_b32_e32 v0, 0xffffc000, v0
	v_lshl_add_u32 v0, v11, 10, v0
	v_and_b32_e32 v1, 1, v12
	v_lshl_or_b32 v0, v1, 6, v0
	v_lshl_add_u32 v168, v13, 1, v0
	v_lshlrev_b32_e32 v0, 13, v8
	v_and_b32_e32 v0, 0xffffc000, v0
	s_waitcnt vmcnt(6)
	v_lshl_add_u32 v0, v9, 10, v0
	v_and_b32_e32 v1, 1, v8
	s_cselect_b64 s[8:9], -1, 0
	v_lshl_or_b32 v0, v1, 6, v0
	s_add_i32 s35, 0, 0x10000
	s_add_i32 s37, 0, 0x14000
	v_mov_b32_e32 v169, v165
	v_lshl_add_u32 v170, v10, 1, v0
	v_mov_b32_e32 v171, v165
	v_add_u32_e32 v182, s35, v181
	v_add_u32_e32 v183, s37, v181
	v_add_u32_e32 v184, 0, v16
	s_mov_b32 s36, 0x3d000000
	s_barrier
	s_branch .LBB0_337

.LBB0_638:
	s_lshl_b32 s8, s8, 5
	v_and_b32_e32 v158, 63, v8
	v_and_b32_e32 v15, 48, v8
	v_lshlrev_b32_e32 v16, 6, v8
	s_movk_i32 s11, 0x3c0
	v_lshlrev_b32_e32 v8, 2, v8
	s_and_b32 s47, s8, 0x60
	s_lshl_b32 s46, s9, 6
	s_lshl_b32 s9, s9, 13
	v_and_or_b32 v15, v16, s11, v15
	v_and_b32_e32 v8, 32, v8
	s_lshl_b32 s8, s47, 7
	v_bitop3_b32 v16, v15, s9, v8 bitop3:0xde
	v_bitop3_b32 v159, s8, v15, v8 bitop3:0xf6
	s_mov_b64 s[8:9], 0x80
	s_add_i32 m0, s42, 0x18000
	v_lshl_add_u64 v[6:7], v[6:7], 0, s[8:9]
	global_load_lds_dwordx4 v[6:7], off
	v_lshl_add_u64 v[4:5], v[4:5], 0, s[8:9]
	s_add_i32 m0, s42, 0x1a000
	s_add_i32 s48, s42, 0x8000
	s_add_i32 s49, s42, 0xa000
	global_load_lds_dwordx4 v[4:5], off
	v_lshl_add_u64 v[0:1], v[0:1], 0, s[8:9]
	s_mov_b32 m0, s48
	s_add_u32 s12, s36, 0x40080
	global_load_lds_dwordx4 v[0:1], off
	v_lshl_add_u64 v[0:1], v[2:3], 0, s[8:9]
	s_mov_b32 m0, s49
	s_addc_u32 s13, s37, 0
	global_load_lds_dwordx4 v[0:1], off
	s_add_i32 m0, s42, 0x1c000
	v_lshl_add_u64 v[0:1], s[12:13], 0, v[130:131]
	global_load_lds_dwordx4 v[0:1], off
	v_lshl_add_u64 v[0:1], s[12:13], 0, v[134:135]
	s_add_i32 m0, s42, 0x1e000
	s_cmpk_lt_u32 s10, 0x100
	global_load_lds_dwordx4 v[0:1], off
	s_waitcnt vmcnt(8)
	s_barrier
	v_lshlrev_b32_e32 v0, 14, v9
	v_and_b32_e32 v0, 0xffff8000, v0
	v_lshl_add_u32 v0, v10, 11, v0
	v_and_b32_e32 v1, 1, v9
	v_lshl_or_b32 v0, v1, 6, v0
	v_lshl_add_u32 v136, v11, 1, v0
	v_lshlrev_b32_e32 v0, 14, v12
	v_and_b32_e32 v0, 0xffff8000, v0
	s_waitcnt vmcnt(6)
	v_lshl_add_u32 v0, v13, 11, v0
	v_and_b32_e32 v1, 1, v12
	v_lshl_or_b32 v0, v1, 6, v0
	s_cselect_b64 s[10:11], -1, 0
	v_mov_b32_e32 v137, v131
	v_lshl_add_u32 v138, v14, 1, v0
	v_mov_b32_e32 v139, v131
	s_add_i32 s51, 0, 0x10000
	s_add_i32 s52, 0, 0x14000
	v_add_u32_e32 v160, 0, v16
	s_mov_b64 s[12:13], 0x20000
	s_mov_b64 s[14:15], 0x24000
	s_mov_b64 s[16:17], 0x28000
	s_mov_b64 s[18:19], 0x2c000
	s_mov_b32 s53, 0
	v_mov_b32_e32 v0, v131
	v_mov_b32_e32 v1, v131
	v_mov_b32_e32 v2, v131
	v_mov_b32_e32 v3, v131
	v_mov_b32_e32 v4, v131
	v_mov_b32_e32 v5, v131
	v_mov_b32_e32 v6, v131
	v_mov_b32_e32 v7, v131
	v_mov_b32_e32 v8, v131
	v_mov_b32_e32 v9, v131
	v_mov_b32_e32 v10, v131
	v_mov_b32_e32 v11, v131
	v_mov_b32_e32 v12, v131
	v_mov_b32_e32 v13, v131
	v_mov_b32_e32 v14, v131
	v_mov_b32_e32 v15, v131
	v_mov_b32_e32 v16, v131
	v_mov_b32_e32 v17, v131
	v_mov_b32_e32 v18, v131
	v_mov_b32_e32 v19, v131
	v_mov_b32_e32 v20, v131
	v_mov_b32_e32 v21, v131
	v_mov_b32_e32 v22, v131
	v_mov_b32_e32 v23, v131
	v_mov_b32_e32 v24, v131
	v_mov_b32_e32 v25, v131
	v_mov_b32_e32 v26, v131
	v_mov_b32_e32 v27, v131
	v_mov_b32_e32 v28, v131
	v_mov_b32_e32 v29, v131
	v_mov_b32_e32 v30, v131
	v_mov_b32_e32 v31, v131
	v_mov_b32_e32 v32, v131
	v_mov_b32_e32 v33, v131
	v_mov_b32_e32 v34, v131
	v_mov_b32_e32 v35, v131
	v_mov_b32_e32 v36, v131
	v_mov_b32_e32 v37, v131
	v_mov_b32_e32 v38, v131
	v_mov_b32_e32 v39, v131
	v_mov_b32_e32 v40, v131
	v_mov_b32_e32 v41, v131
	v_mov_b32_e32 v42, v131
	v_mov_b32_e32 v43, v131
	v_mov_b32_e32 v44, v131
	v_mov_b32_e32 v45, v131
	v_mov_b32_e32 v46, v131
	v_mov_b32_e32 v47, v131
	v_mov_b32_e32 v48, v131
	v_mov_b32_e32 v49, v131
	v_mov_b32_e32 v50, v131
	v_mov_b32_e32 v51, v131
	v_mov_b32_e32 v52, v131
	v_mov_b32_e32 v53, v131
	v_mov_b32_e32 v54, v131
	v_mov_b32_e32 v55, v131
	v_mov_b32_e32 v56, v131
	v_mov_b32_e32 v57, v131
	v_mov_b32_e32 v58, v131
	v_mov_b32_e32 v59, v131
	v_mov_b32_e32 v60, v131
	v_mov_b32_e32 v61, v131
	v_mov_b32_e32 v62, v131
	v_mov_b32_e32 v63, v131
	v_mov_b32_e32 v64, v131
	v_mov_b32_e32 v65, v131
	v_mov_b32_e32 v66, v131
	v_mov_b32_e32 v67, v131
	v_mov_b32_e32 v68, v131
	v_mov_b32_e32 v69, v131
	v_mov_b32_e32 v70, v131
	v_mov_b32_e32 v71, v131
	v_mov_b32_e32 v72, v131
	v_mov_b32_e32 v73, v131
	v_mov_b32_e32 v74, v131
	v_mov_b32_e32 v75, v131
	v_mov_b32_e32 v76, v131
	v_mov_b32_e32 v77, v131
	v_mov_b32_e32 v78, v131
	v_mov_b32_e32 v79, v131
	v_mov_b32_e32 v80, v131
	v_mov_b32_e32 v81, v131
	v_mov_b32_e32 v82, v131
	v_mov_b32_e32 v83, v131
	v_mov_b32_e32 v84, v131
	v_mov_b32_e32 v85, v131
	v_mov_b32_e32 v86, v131
	v_mov_b32_e32 v87, v131
	v_mov_b32_e32 v88, v131
	v_mov_b32_e32 v89, v131
	v_mov_b32_e32 v90, v131
	v_mov_b32_e32 v91, v131
	v_mov_b32_e32 v92, v131
	v_mov_b32_e32 v93, v131
	v_mov_b32_e32 v94, v131
	v_mov_b32_e32 v95, v131
	v_mov_b32_e32 v96, v131
	v_mov_b32_e32 v97, v131
	v_mov_b32_e32 v98, v131
	v_mov_b32_e32 v99, v131
	v_mov_b32_e32 v100, v131
	v_mov_b32_e32 v101, v131
	v_mov_b32_e32 v102, v131
	v_mov_b32_e32 v103, v131
	v_mov_b32_e32 v104, v131
	v_mov_b32_e32 v105, v131
	v_mov_b32_e32 v106, v131
	v_mov_b32_e32 v107, v131
	v_mov_b32_e32 v108, v131
	v_mov_b32_e32 v109, v131
	v_mov_b32_e32 v110, v131
	v_mov_b32_e32 v111, v131
	v_mov_b32_e32 v112, v131
	v_mov_b32_e32 v113, v131
	v_mov_b32_e32 v114, v131
	v_mov_b32_e32 v115, v131
	v_mov_b32_e32 v116, v131
	v_mov_b32_e32 v117, v131
	v_mov_b32_e32 v118, v131
	v_mov_b32_e32 v119, v131
	v_mov_b32_e32 v120, v131
	v_mov_b32_e32 v121, v131
	v_mov_b32_e32 v122, v131
	v_mov_b32_e32 v123, v131
	v_mov_b32_e32 v124, v131
	v_mov_b32_e32 v125, v131
	v_mov_b32_e32 v126, v131
	v_mov_b32_e32 v127, v131
	s_barrier
	s_branch .LBB0_641

.LBB0_782:
	s_and_b32 s41, s10, 3
	s_lshl_b32 s42, s11, 6
	s_lshl_b32 s13, s11, 13
	s_mov_b64 s[10:11], 0x80
	s_add_i32 m0, s37, 0x18000
	v_lshl_add_u64 v[6:7], v[6:7], 0, s[10:11]
	s_lshl_b32 s43, s41, 5
	s_lshl_b32 s16, s41, 12
	global_load_lds_dwordx4 v[6:7], off
	v_lshl_add_u64 v[4:5], v[4:5], 0, s[10:11]
	s_add_i32 m0, s37, 0x1a000
	s_add_i32 s44, s37, 0x8000
	s_add_i32 s45, s37, 0xa000
	global_load_lds_dwordx4 v[4:5], off
	v_lshl_add_u64 v[0:1], v[0:1], 0, s[10:11]
	s_mov_b32 m0, s44
	s_add_u32 s14, s28, 0x40080
	global_load_lds_dwordx4 v[0:1], off
	v_lshl_add_u64 v[0:1], v[2:3], 0, s[10:11]
	s_mov_b32 m0, s45
	s_addc_u32 s15, s29, 0
	global_load_lds_dwordx4 v[0:1], off
	s_add_i32 m0, s37, 0x1c000
	v_lshl_add_u64 v[0:1], s[14:15], 0, v[130:131]
	global_load_lds_dwordx4 v[0:1], off
	v_lshl_add_u64 v[0:1], s[14:15], 0, v[134:135]
	s_add_i32 m0, s37, 0x1e000
	s_movk_i32 s14, 0x3c0
	global_load_lds_dwordx4 v[0:1], off
	s_waitcnt vmcnt(8)
	s_barrier
	v_and_b32_e32 v0, 48, v8
	v_lshlrev_b32_e32 v1, 6, v8
	v_and_or_b32 v0, v1, s14, v0
	v_lshlrev_b32_e32 v1, 2, v8
	v_and_b32_e32 v1, 32, v1
	v_bitop3_b32 v2, v0, s13, v1 bitop3:0xde
	v_bitop3_b32 v145, v0, s16, v1 bitop3:0xde
	v_lshlrev_b32_e32 v0, 14, v9
	v_and_b32_e32 v0, 0xffff8000, v0
	v_lshl_add_u32 v0, v10, 11, v0
	v_and_b32_e32 v1, 1, v9
	v_lshl_or_b32 v0, v1, 6, v0
	v_lshl_add_u32 v136, v11, 1, v0
	v_lshlrev_b32_e32 v0, 14, v12
	v_and_b32_e32 v0, 0xffff8000, v0
	v_lshl_add_u32 v0, v13, 11, v0
	v_and_b32_e32 v1, 1, v12
	s_waitcnt vmcnt(6)
	s_cmpk_lt_u32 s12, 0x100
	v_lshl_or_b32 v0, v1, 6, v0
	s_cselect_b64 s[12:13], -1, 0
	v_lshl_add_u32 v138, v14, 1, v0
	s_add_i32 s46, 0, 0x10000
	s_add_i32 s47, 0, 0x14000
	v_mbcnt_lo_u32_b32 v0, -1, 0
	v_and_b32_e32 v144, 63, v8
	v_mov_b32_e32 v137, v131
	v_mov_b32_e32 v139, v131
	v_add_u32_e32 v146, s46, v145
	v_add_u32_e32 v147, s47, v145
	v_add_u32_e32 v148, 0, v2
	v_mbcnt_hi_u32_b32 v149, -1, v0
	s_mov_b32 s48, 0
	s_barrier
	s_branch .LBB0_785

.LBB0_873:
	s_lshl_b32 s8, s8, 5
	s_lshl_b32 s40, s9, 6
	s_lshl_b32 s14, s9, 13
	s_and_b32 s41, s8, 0x60
	s_mov_b64 s[8:9], 0x80
	s_add_i32 m0, s21, 0x18000
	v_lshl_add_u64 v[6:7], v[6:7], 0, s[8:9]
	s_lshl_b32 s15, s41, 7
	global_load_lds_dwordx4 v[6:7], off
	v_lshl_add_u64 v[4:5], v[4:5], 0, s[8:9]
	s_add_i32 m0, s21, 0x1a000
	s_add_i32 s42, s21, 0x8000
	s_add_i32 s43, s21, 0xa000
	global_load_lds_dwordx4 v[4:5], off
	v_lshl_add_u64 v[0:1], v[0:1], 0, s[8:9]
	s_mov_b32 m0, s42
	s_add_u32 s12, s28, 0x40080
	global_load_lds_dwordx4 v[0:1], off
	v_lshl_add_u64 v[0:1], v[2:3], 0, s[8:9]
	s_mov_b32 m0, s43
	s_addc_u32 s13, s29, 0
	global_load_lds_dwordx4 v[0:1], off
	s_add_i32 m0, s21, 0x1c000
	v_lshl_add_u64 v[0:1], s[12:13], 0, v[132:133]
	global_load_lds_dwordx4 v[0:1], off
	v_lshl_add_u64 v[0:1], s[12:13], 0, v[128:129]
	s_add_i32 m0, s21, 0x1e000
	s_sext_i32_i8 s47, s10
	global_load_lds_dwordx4 v[0:1], off
	s_waitcnt vmcnt(8)
	s_barrier
	v_and_b32_e32 v0, 48, v9
	v_lshlrev_b32_e32 v1, 6, v9
	s_movk_i32 s10, 0x3c0
	v_and_or_b32 v0, v1, s10, v0
	v_lshlrev_b32_e32 v1, 2, v9
	v_and_b32_e32 v1, 32, v1
	v_bitop3_b32 v2, v0, s14, v1 bitop3:0xde
	v_bitop3_b32 v145, s15, v0, v1 bitop3:0xf6
	v_lshlrev_b32_e32 v0, 14, v13
	v_and_b32_e32 v0, 0xffff8000, v0
	v_lshl_add_u32 v0, v12, 11, v0
	v_and_b32_e32 v1, 1, v13
	v_lshl_or_b32 v0, v1, 6, v0
	v_lshl_add_u32 v136, v14, 1, v0
	v_lshlrev_b32_e32 v0, 14, v8
	v_and_b32_e32 v0, 0xffff8000, v0
	s_waitcnt vmcnt(6)
	s_cmpk_lt_u32 s11, 0x100
	v_lshl_add_u32 v0, v10, 11, v0
	v_and_b32_e32 v1, 1, v8
	s_cselect_b64 s[10:11], -1, 0
	v_lshl_or_b32 v0, v1, 6, v0
	s_add_i32 s44, 0, 0x10000
	s_add_i32 s45, 0, 0x14000
	v_and_b32_e32 v144, 63, v9
	v_mov_b32_e32 v137, v133
	v_lshl_add_u32 v138, v11, 1, v0
	v_mov_b32_e32 v139, v133
	v_add_u32_e32 v146, s44, v145
	v_add_u32_e32 v147, s45, v145
	v_add_u32_e32 v148, 0, v2
	v_mov_b32_e32 v149, 0x358637bd
	s_barrier
	s_branch .LBB0_876

.LBB0_950:
	s_add_u32 s8, s68, 0x300000
	s_addc_u32 s9, s69, 0
	s_and_b32 s41, s10, 3
	s_lshl_b32 s42, s11, 6
	s_lshl_b32 s13, s11, 13
	s_mov_b64 s[10:11], 0x80
	s_add_i32 m0, s37, 0x18000
	v_lshl_add_u64 v[6:7], v[6:7], 0, s[10:11]
	s_lshl_b32 s43, s41, 5
	s_lshl_b32 s16, s41, 12
	global_load_lds_dwordx4 v[6:7], off
	v_lshl_add_u64 v[4:5], v[4:5], 0, s[10:11]
	s_add_i32 m0, s37, 0x1a000
	s_add_i32 s44, s37, 0x8000
	s_add_i32 s45, s37, 0xa000
	global_load_lds_dwordx4 v[4:5], off
	v_lshl_add_u64 v[0:1], v[0:1], 0, s[10:11]
	s_mov_b32 m0, s44
	s_add_u32 s14, s28, 0x100080
	global_load_lds_dwordx4 v[0:1], off
	v_lshl_add_u64 v[0:1], v[2:3], 0, s[10:11]
	s_mov_b32 m0, s45
	s_addc_u32 s15, s29, 0
	global_load_lds_dwordx4 v[0:1], off
	s_add_i32 m0, s37, 0x1c000
	v_lshl_add_u64 v[0:1], s[14:15], 0, v[130:131]
	global_load_lds_dwordx4 v[0:1], off
	v_lshl_add_u64 v[0:1], s[14:15], 0, v[134:135]
	s_add_i32 m0, s37, 0x1e000
	s_movk_i32 s14, 0x3c0
	global_load_lds_dwordx4 v[0:1], off
	s_waitcnt vmcnt(8)
	s_barrier
	v_and_b32_e32 v0, 48, v8
	v_lshlrev_b32_e32 v1, 6, v8
	v_and_or_b32 v0, v1, s14, v0
	v_lshlrev_b32_e32 v1, 2, v8
	v_and_b32_e32 v1, 32, v1
	v_bitop3_b32 v2, v0, s13, v1 bitop3:0xde
	v_bitop3_b32 v145, v0, s16, v1 bitop3:0xde
	v_lshlrev_b32_e32 v0, 16, v9
	v_and_b32_e32 v0, 0xfffe0000, v0
	v_lshl_add_u32 v0, v10, 13, v0
	v_and_b32_e32 v1, 1, v9
	v_lshl_or_b32 v0, v1, 6, v0
	v_lshl_add_u32 v136, v11, 1, v0
	v_lshlrev_b32_e32 v0, 16, v12
	v_and_b32_e32 v0, 0xfffe0000, v0
	v_lshl_add_u32 v0, v13, 13, v0
	v_and_b32_e32 v1, 1, v12
	s_waitcnt vmcnt(6)
	s_cmpk_lt_u32 s12, 0x100
	v_lshl_or_b32 v0, v1, 6, v0
	s_cselect_b64 s[12:13], -1, 0
	v_lshl_add_u32 v138, v14, 1, v0
	s_add_i32 s46, 0, 0x10000
	s_add_i32 s47, 0, 0x14000
	v_mbcnt_lo_u32_b32 v0, -1, 0
	v_and_b32_e32 v144, 63, v8
	v_mov_b32_e32 v137, v131
	v_mov_b32_e32 v139, v131
	v_add_u32_e32 v146, s46, v145
	v_add_u32_e32 v147, s47, v145
	v_add_u32_e32 v148, 0, v2
	v_mbcnt_hi_u32_b32 v149, -1, v0
	s_mov_b32 s48, 0
	s_barrier
	s_branch .LBB0_953

.LBB0_1041:
	s_mov_b64 s[10:11], 0x80
	s_add_i32 m0, s46, 0x18000
	v_lshl_add_u64 v[8:9], v[8:9], 0, s[10:11]
	global_load_lds_dwordx4 v[8:9], off
	v_lshl_add_u64 v[4:5], v[4:5], 0, s[10:11]
	s_add_i32 m0, s46, 0x1a000
	s_add_i32 s52, s46, 0x8000
	global_load_lds_dwordx4 v[4:5], off
	v_lshl_add_u64 v[4:5], v[6:7], 0, s[10:11]
	s_mov_b32 m0, s52
	s_add_i32 s53, s46, 0xa000
	global_load_lds_dwordx4 v[4:5], off
	v_lshl_add_u64 v[4:5], v[10:11], 0, s[10:11]
	s_mov_b32 m0, s53
	v_lshl_add_u64 v[2:3], v[2:3], 0, s[10:11]
	global_load_lds_dwordx4 v[4:5], off
	s_add_i32 m0, s46, 0x1c000
	v_lshl_add_u64 v[0:1], v[0:1], 0, s[10:11]
	global_load_lds_dwordx4 v[2:3], off
	s_add_i32 m0, s46, 0x1e000
	s_sext_i32_i8 s23, s12
	global_load_lds_dwordx4 v[0:1], off
	s_waitcnt vmcnt(8)
	s_barrier
	s_lshr_b32 s5, s5, 26
	v_and_b32_e32 v0, 48, v12
	v_lshlrev_b32_e32 v1, 6, v12
	s_movk_i32 s12, 0x3c0
	s_add_i32 s5, s4, s5
	v_and_or_b32 v0, v1, s12, v0
	v_lshlrev_b32_e32 v1, 2, v12
	s_ashr_i32 s54, s5, 6
	s_lshl_b32 s5, s15, 13
	v_and_b32_e32 v1, 32, v1
	v_bitop3_b32 v2, v0, s5, v1 bitop3:0xde
	s_lshl_b32 s5, s14, 5
	s_and_b32 s56, s5, 0x60
	s_lshl_b32 s5, s56, 7
	s_lshl_b32 s55, s15, 6
	v_bitop3_b32 v141, s5, v0, v1 bitop3:0xf6
	v_add_u32_e32 v0, v18, v16
	s_cmp_gt_i32 s4, 63
	v_add_lshl_u32 v0, v0, v17, 1
	v_mov_b32_e32 v1, v133
	s_cselect_b64 s[4:5], -1, 0
	s_add_i32 s57, s54, -2
	v_lshl_add_u64 v[136:137], s[6:7], 0, v[0:1]
	v_add_u32_e32 v0, v15, v13
	s_waitcnt vmcnt(6)
	s_cmpk_lt_u32 s13, 0x100
	v_add_lshl_u32 v0, v0, v14, 1
	s_cselect_b64 s[12:13], -1, 0
	v_lshl_add_u64 v[138:139], s[6:7], 0, v[0:1]
	v_cndmask_b32_e64 v0, 0, 1, s[4:5]
	s_add_i32 s58, 0, 0x10000
	s_add_i32 s59, 0, 0x14000
	v_and_b32_e32 v140, 63, v12
	v_cmp_ne_u32_e64 s[4:5], 1, v0
	v_add_u32_e32 v142, s58, v141
	v_add_u32_e32 v143, s59, v141
	v_add_u32_e32 v144, 0, v2
	s_mov_b64 s[14:15], 0x40000
	s_mov_b32 s60, 0x40000
	s_mov_b64 s[16:17], 0x48000
	s_mov_b32 s61, 0x48000
	s_mov_b64 s[18:19], 0x50000
	s_mov_b32 s62, 0x50000
	s_mov_b64 s[20:21], 0x58000
	s_mov_b32 s63, 0x58000
	s_barrier
	s_branch .LBB0_1044

.LBB0_1064:
	s_add_u32 s6, s68, 0x300000
	s_addc_u32 s7, s69, 0
	s_add_u32 s8, s68, 0x400000
	s_addc_u32 s9, s69, 0
	s_and_b32 s43, s0, 3
	s_lshl_b32 s44, s10, 6
	s_lshl_b32 s0, s10, 13
	s_mov_b64 s[10:11], 0x80
	s_add_i32 m0, s39, 0x18000
	v_lshl_add_u64 v[6:7], v[6:7], 0, s[10:11]
	s_lshl_b32 s45, s43, 5
	s_lshl_b32 s13, s43, 12
	global_load_lds_dwordx4 v[6:7], off
	v_lshl_add_u64 v[4:5], v[4:5], 0, s[10:11]
	s_add_i32 m0, s39, 0x1a000
	s_add_i32 s46, s39, 0x8000
	s_add_i32 s47, s39, 0xa000
	global_load_lds_dwordx4 v[4:5], off
	v_lshl_add_u64 v[0:1], v[0:1], 0, s[10:11]
	s_mov_b32 m0, s46
	s_add_u32 s14, s30, 0x40080
	global_load_lds_dwordx4 v[0:1], off
	v_lshl_add_u64 v[0:1], v[2:3], 0, s[10:11]
	s_mov_b32 m0, s47
	s_addc_u32 s15, s31, 0
	global_load_lds_dwordx4 v[0:1], off
	s_add_i32 m0, s39, 0x1c000
	v_lshl_add_u64 v[0:1], s[14:15], 0, v[130:131]
	global_load_lds_dwordx4 v[0:1], off
	v_lshl_add_u64 v[0:1], s[14:15], 0, v[134:135]
	s_add_i32 m0, s39, 0x1e000
	s_movk_i32 s14, 0x3c0
	global_load_lds_dwordx4 v[0:1], off
	s_waitcnt vmcnt(8)
	s_barrier
	v_and_b32_e32 v0, 48, v8
	v_lshlrev_b32_e32 v1, 6, v8
	v_and_or_b32 v0, v1, s14, v0
	v_lshlrev_b32_e32 v1, 2, v8
	v_and_b32_e32 v1, 32, v1
	v_bitop3_b32 v2, v0, s0, v1 bitop3:0xde
	v_bitop3_b32 v149, v0, s13, v1 bitop3:0xde
	v_lshlrev_b32_e32 v0, 14, v9
	v_and_b32_e32 v0, 0xffff8000, v0
	v_lshl_add_u32 v0, v10, 11, v0
	v_and_b32_e32 v1, 1, v9
	v_lshl_or_b32 v0, v1, 6, v0
	v_lshl_add_u32 v136, v11, 1, v0
	v_lshlrev_b32_e32 v0, 14, v12
	v_and_b32_e32 v0, 0xffff8000, v0
	v_lshl_add_u32 v0, v13, 11, v0
	v_and_b32_e32 v1, 1, v12
	s_waitcnt vmcnt(6)
	s_cmpk_lt_u32 s12, 0x100
	v_lshl_or_b32 v0, v1, 6, v0
	s_cselect_b64 s[12:13], -1, 0
	v_lshl_add_u32 v138, v14, 1, v0
	s_add_i32 s48, 0, 0x10000
	s_add_i32 s49, 0, 0x14000
	v_mbcnt_lo_u32_b32 v0, -1, 0
	v_and_b32_e32 v148, 63, v8
	v_mov_b32_e32 v137, v131
	v_mov_b32_e32 v139, v131
	v_add_u32_e32 v150, s48, v149
	v_add_u32_e32 v151, s49, v149
	v_add_u32_e32 v152, 0, v2
	v_mbcnt_hi_u32_b32 v153, -1, v0
	v_mov_b32_e32 v154, 0x358637bd
	s_mov_b32 s50, 0
	s_barrier
	s_branch .LBB0_1067
